# retention scan: logical wave roles permuted so each SIMD hosts one score-computing (wk=0) and one wk=1 wave
# baseline (speedup 1.0000x reference)
; __device__ __forceinline__ char* WS(const Params& p) { return p.ws + opaque0(); }
; template <int MODE>
; __device__ void scan_unit(int swave, const Params& p, int j, int b, int h, int dir, char* shm) {
;     ...
;   const int tid = tidx, lane = tid & 63, w = tid >> 6, r = lane & 15, q4 = lane >> 4;
;   const int wk = w % KS, wv = w / KS, slab = wk * 64, vt0 = wv * NVT;
;   const int hh = MODE == 1 ? 4 + h : h;
;   bf16_t* O = (bf16_t*)(WS(p) + OFF_OFB + (dir ? (MODE == 2 ? OFB_OB_ODD : OFB_OB_EVEN) : 0)) + hh * DV;
;   const size_t rowbase = (size_t)b * SEQ;
;   const int ti = lane & 15, dp = (tid >> 4) * 2;
;   float wa2r[32]; float bav0 = 0.f, bav1 = 0.f, lbv0 = 0.f, lbv1 = 0.f, lg = 0.f;
;   const float2* rope = (const float2*)(WS(p) + OFF_MISC + MISC_ROPE);
;   if (MODE == 0) {
;     const float* wa2 = INP(p, 6) + ((size_t)(j * 2 + dir) * 16) * 256 + h * 64 + dp;
; #pragma unroll
;     for (int rr = 0; rr < 16; ++rr) { const float2 t2 = *(const float2*)(wa2 + rr * 256); wa2r[2 * rr] = t2.x; wa2r[2 * rr + 1] = t2.y; }
;     const float2 bb = *(const float2*)(INP(p, 7) + (j * 2 + dir) * 256 + h * 64 + dp);
;     bav0 = bb.x; bav1 = bb.y;
;   } else if (MODE == 1) {
;     if (j > 0) {
;       const float2 l0 = *(const float2*)(INP(p, 9) + (dir * 2 + 0) * 256 + h * 64 + dp), l1 = *(const float2*)(INP(p, 9) + (dir * 2 + 1) * 256 + h * 64 + dp);
;       lbv0 = 1.f / (1.f + __expf(l0.x - l1.x)); lbv1 = 1.f / (1.f + __expf(l0.y - l1.y));
;     }
;   } else {
;     lg = log1pf(-exp2f((dir ? -5.5f : -5.0f) - (float)h));
;   }
;   const int vg = tid >> 4;
;   const float ret_ein = __expf(lg * (float)(ti + 1)), ret_eti = __expf(-lg * (float)(ti + 1)), ret_eout = __expf(lg * (float)(15 - ti)), ret_dd = __expf(lg * 16.f);
;   struct Raw { unsigned q, k, q2, k2; uint4 lr0, lr1; uint2 v; unsigned v30, v31, v32; float4 cs; };
;   auto tokof = [&](int c, int i) { int t = c * 16 + i; return dir ? (SEQ - 1 - t) : t; };
;   auto load_raw = [&](int c, Raw& R) {
;     const int tok = tokof(c, ti);
;     const bf16_t* row = P + (rowbase + tok) * LDP;
;     if (MODE == 0) {
;       R.q = *(const unsigned*)(row + E_GQ + h * 64 + dp); R.k = *(const unsigned*)(row + E_GK + h * 64 + dp);
;       const uint4* lrp = (const uint4*)(row + (dir ? E_GLB : E_GLF));
;       R.lr0 = lrp[0]; R.lr1 = lrp[1];
;       R.v = *(const uint2*)(row + E_GV + h * 128 + vg * 4);
;     } else if (MODE == 1) {
.LBB0_562:
	s_and_b64 vcc, exec, s[0:1]
	s_cbranch_vccz .LBB0_627
	v_readlane_b32 s0, v246, 4
	v_readlane_b32 s12, v248, 8
	s_ashr_i32 s4, s0, 3
	s_bfe_u32 s8, s0, 0x20001
	s_and_b32 s5, s0, 1
	v_and_b32_e32 v111, 0xc0, v147
	v_bfe_u32 v0, v147, 8, 1
	v_lshlrev_b32_e32 v111, 1, v111
	v_lshl_or_b32 v111, v0, 6, v111
	v_and_or_b32 v111, v147, 63, v111
	s_mov_b64 s[0:1], 0
	v_readlane_b32 s14, v248, 10
	v_readlane_b32 s15, v248, 11
	s_add_u32 s7, s14, s0
	s_addc_u32 s9, s15, s1
	s_cmp_eq_u32 s5, 0
	s_mov_b64 s[2:3], 0
	s_cselect_b64 s[0:1], -1, 0
	s_mov_b64 s[10:11], 0
	s_ashr_i32 s5, s4, 31
	v_cndmask_b32_e64 v0, v150, v151, s[0:1]
	v_cvt_f32_ubyte0_e32 v1, s8
	s_add_u32 s12, s14, s10
	v_sub_f32_e32 v0, v0, v1
	s_mov_b32 s10, 0xc2fc0000
	v_cmp_gt_f32_e32 vcc, s10, v0
	v_readlane_b32 s13, v248, 9
	s_addc_u32 s13, s15, s11
	v_cndmask_b32_e32 v1, 0, v152, vcc
	v_add_f32_e32 v0, v0, v1
	v_exp_f32_e32 v0, v0
	s_and_b64 s[10:11], vcc, exec
	s_cselect_b32 s10, 0xffffffc0, 0
	v_ashrrev_i32_e32 v2, 3, v111
	v_ldexp_f32 v36, v0, s10
	s_waitcnt vmcnt(0)
	v_sub_f32_e32 v4, 1.0, v36
	v_add_f32_e32 v0, -1.0, v4
	v_sub_f32_e32 v1, v0, v4
	v_add_f32_e32 v1, 1.0, v1
	v_sub_f32_e64 v0, -v36, v0
	v_add_f32_e32 v5, v0, v1
	v_frexp_mant_f32_e32 v6, v4
	v_cvt_f64_f32_e32 v[0:1], v4
	s_mov_b32 s10, 0x3f2aaaab
	v_frexp_exp_i32_f64_e32 v0, v[0:1]
	v_cmp_gt_f32_e32 vcc, s10, v6
	s_mov_b32 s10, 0x3f317218
	s_add_u32 s44, s7, 0xc000000
	s_waitcnt vmcnt(0)
	v_subbrev_co_u32_e32 v10, vcc, 0, v0, vcc
	v_sub_u32_e32 v0, 0, v10
	v_ldexp_f32 v1, v4, v0
	v_add_f32_e32 v4, -1.0, v1
	v_add_f32_e32 v6, 1.0, v1
	v_ldexp_f32 v0, v5, v0
	v_add_f32_e32 v5, 1.0, v4
	v_add_f32_e32 v7, -1.0, v6
	v_sub_f32_e32 v5, v1, v5
	v_sub_f32_e32 v1, v1, v7
	v_add_f32_e32 v5, v0, v5
	v_add_f32_e32 v0, v0, v1
	v_add_f32_e32 v11, v6, v0
	v_rcp_f32_e32 v13, v11
	v_sub_f32_e32 v1, v11, v6
	v_sub_f32_e32 v12, v0, v1
	v_add_f32_e32 v1, v4, v5
	v_mul_f32_e32 v15, v1, v13
	v_sub_f32_e32 v0, v1, v4
	v_mul_f32_e32 v4, v11, v15
	v_fma_f32 v6, v15, v11, -v4
	v_fmac_f32_e32 v6, v15, v12
	v_sub_f32_e32 v14, v5, v0
	v_add_f32_e32 v0, v4, v6
	v_sub_f32_e32 v5, v1, v0
	v_pk_add_f32 v[8:9], v[0:1], v[4:5] neg_lo:[0,1] neg_hi:[0,1]
	v_mov_b32_e32 v7, v0
	v_pk_add_f32 v[0:1], v[8:9], v[6:7] neg_lo:[0,1] neg_hi:[0,1]
	s_movk_i32 s7, 0x7ff
	v_add_f32_e32 v1, v14, v1
	v_add_f32_e32 v0, v0, v1
	v_add_f32_e32 v1, v5, v0
	v_mul_f32_e32 v14, v13, v1
	v_mul_f32_e32 v4, v11, v14
	v_fma_f32 v6, v14, v11, -v4
	v_fmac_f32_e32 v6, v14, v12
	v_sub_f32_e32 v5, v5, v1
	v_add_f32_e32 v11, v0, v5
	v_add_f32_e32 v0, v4, v6
	v_sub_f32_e32 v5, v1, v0
	v_pk_add_f32 v[8:9], v[0:1], v[4:5] neg_lo:[0,1] neg_hi:[0,1]
	v_mov_b32_e32 v7, v0
	v_pk_add_f32 v[0:1], v[8:9], v[6:7] neg_lo:[0,1] neg_hi:[0,1]
	v_and_b32_e32 v116, 15, v111
	v_add_f32_e32 v1, v11, v1
	v_add_f32_e32 v0, v0, v1
	v_add_f32_e32 v1, v15, v14
	v_add_f32_e32 v0, v5, v0
	v_sub_f32_e32 v4, v1, v15
	v_mul_f32_e32 v0, v13, v0
	v_sub_f32_e32 v4, v14, v4
	v_add_f32_e32 v4, v4, v0
	v_add_f32_e32 v6, v1, v4
	v_mul_f32_e32 v7, v6, v6
	v_fmamk_f32 v0, v7, 0x3e9b6dac, v148
	v_fmaak_f32 v135, v7, v0, 0x3f2aaada
	v_cvt_f32_i32_e32 v0, v10
	v_sub_f32_e32 v1, v6, v1
	v_sub_f32_e32 v1, v4, v1
	v_ldexp_f32 v8, v1, 1
	v_mul_f32_e32 v1, v6, v7
	v_ldexp_f32 v5, v6, 1
	v_pk_mul_f32 v[6:7], v[0:1], v[134:135]
	v_and_b32_e32 v12, -2, v2
	v_fma_f32 v4, v0, s10, -v6
	v_fmac_f32_e32 v4, 0xb102e308, v0
	v_pk_add_f32 v[0:1], v[6:7], v[4:5]
	v_bitop3_b32 v2, v111, s7, 15 bitop3:0x6c
	v_sub_f32_e32 v5, v1, v5
	v_sub_f32_e32 v5, v7, v5
	s_addc_u32 s45, s9, 0
	s_lshl_b64 s[18:19], s[4:5], 11
	v_cndmask_b32_e64 v2, v2, v116, s[0:1]
	v_add_f32_e32 v17, v8, v5
	v_or_b32_e32 v5, s18, v2
	v_mov_b64_e32 v[18:19], s[44:45]
	s_add_u32 s4, s12, 0x1eb9c000
	v_mad_u64_u32 v[8:9], s[10:11], v5, s55, v[18:19]
	s_addc_u32 s5, s13, 0
	v_ashrrev_i32_e32 v11, 4, v111
	v_mad_i32_i24 v9, s19, v155, v9
	s_lshl_b32 s94, s8, 8
	v_ashrrev_i32_e32 v13, 31, v12
	s_mul_i32 s6, s8, 0xc0
	v_lshl_add_u64 v[14:15], v[8:9], 0, s[94:95]
	v_lshlrev_b64 v[118:119], 1, v[12:13]
	v_mul_lo_u32 v22, v11, 6
	v_lshl_add_u64 v[14:15], v[14:15], 0, v[118:119]
	v_lshlrev_b32_e32 v2, 9, v2
	s_lshl_b32 s46, s6, 1
	s_mov_b32 s47, s95
	v_ashrrev_i32_e32 v23, 31, v22
	s_barrier
; template <int MODE>
; __device__ void scan_unit(int swave, const Params& p, int j, int b, int h, int dir, char* shm) {
;     ...
;   const float ret_ein = __expf(lg * (float)(ti + 1)), ret_eti = __expf(-lg * (float)(ti + 1)), ret_eout = __expf(lg * (float)(15 - ti)), ret_dd = __expf(lg * 16.f);
;   struct Raw { unsigned q, k, q2, k2; uint4 lr0, lr1; uint2 v; unsigned v30, v31, v32; float4 cs; };
;   auto tokof = [&](int c, int i) { int t = c * 16 + i; return dir ? (SEQ - 1 - t) : t; };
;   auto load_raw = [&](int c, Raw& R) {
;     const int tok = tokof(c, ti);
;     const bf16_t* row = P + (rowbase + tok) * LDP;
;     if (MODE == 0) {
;       R.q = *(const unsigned*)(row + E_GQ + h * 64 + dp); R.k = *(const unsigned*)(row + E_GK + h * 64 + dp);
;       const uint4* lrp = (const uint4*)(row + (dir ? E_GLB : E_GLF));
;       R.lr0 = lrp[0]; R.lr1 = lrp[1];
;       R.v = *(const uint2*)(row + E_GV + h * 128 + vg * 4);
;     } else if (MODE == 1) {
;       R.q = *(const unsigned*)(row + E_HQ + h * 64 + dp); R.k = *(const unsigned*)(row + (dir ? E_HZB : E_HZF) + h * 64 + dp);
;       R.v = *(const uint2*)(row + E_HI + h * 128 + vg * 4);
;     } else {
;       R.q = *(const unsigned*)(row + O_RQ + h * 128 + dp); R.q2 = *(const unsigned*)(row + O_RQ + h * 128 + 64 + dp);
;       R.k = *(const unsigned*)(row + O_RK + h * 128 + dp); R.k2 = *(const unsigned*)(row + O_RK + h * 128 + 64 + dp);
;       R.cs = *(const float4*)(rope + tok * 64 + dp);
;       const unsigned* vp = (const unsigned*)(row + O_RV + h * 192 + vg * 6);
;       R.v30 = vp[0]; R.v31 = vp[1]; R.v32 = vp[2];
;     ...
;       const float KSC = 0.08838834764831845f;
;       const float qx0 = lo_bf(R.q), qx1 = hi_bf(R.q), qy0 = lo_bf(R.q2), qy1 = hi_bf(R.q2);
;       const float kx0 = lo_bf(R.k) * KSC, kx1 = hi_bf(R.k) * KSC, ky0 = lo_bf(R.k2) * KSC, ky1 = hi_bf(R.k2) * KSC;
;       const float c0 = R.cs.x, sn0 = R.cs.y, c1 = R.cs.z, sn1 = R.cs.w;
;       const float qa0 = qx0 * c0 - qy0 * sn0, qb0 = qx0 * sn0 + qy0 * c0, qa1 = qx1 * c1 - qy1 * sn1, qb1 = qx1 * sn1 + qy1 * c1;
;       const float ka0 = kx0 * c0 - ky0 * sn0, kb0 = kx0 * sn0 + ky0 * c0, ka1 = kx1 * c1 - ky1 * sn1, kb1 = kx1 * sn1 + ky1 * c1;
;       const float ein = ret_ein, eti = ret_eti, eout = ret_eout;
;       *(unsigned*)(qin + ti * QS + dp) = pk2(qa0 * ein, qa1 * ein); *(unsigned*)(qin + ti * QS + 64 + dp) = pk2(qb0 * ein, qb1 * ein);
	global_load_dword v37, v[14:15], off
	global_load_dword v38, v[14:15], off offset:128
	global_load_dword v39, v[14:15], off offset:1024
	global_load_dword v40, v[14:15], off offset:1152
	v_lshl_add_u64 v[20:21], s[4:5], 0, v[2:3]
	v_lshlrev_b64 v[14:15], 3, v[12:13]
	v_lshl_add_u64 v[8:9], v[8:9], 0, s[46:47]
	v_lshlrev_b64 v[122:123], 1, v[22:23]
	v_mov_b32_e32 v16, v6
	v_lshl_add_u64 v[20:21], v[20:21], 0, v[14:15]
	v_lshl_add_u64 v[8:9], v[8:9], 0, v[122:123]
	v_pk_add_f32 v[6:7], v[0:1], v[6:7] neg_lo:[0,1] neg_hi:[0,1]
	global_load_dwordx3 v[8:10], v[8:9], off offset:2048
	s_nop 0
	global_load_dwordx4 v[26:29], v[20:21], off
	v_pk_add_f32 v[20:21], v[0:1], v[16:17]
	v_mov_b32_e32 v5, v0
	v_mov_b32_e32 v7, v21
	v_pk_add_f32 v[30:31], v[4:5], v[6:7] neg_lo:[0,1] neg_hi:[0,1]
	v_pk_add_f32 v[4:5], v[4:5], v[6:7]
	v_mov_b32_e32 v24, v1
	v_pk_add_f32 v[6:7], v[4:5], v[0:1] op_sel:[1,0] op_sel_hi:[0,1] neg_lo:[0,1] neg_hi:[0,1]
	v_pk_add_f32 v[22:23], v[20:21], v[6:7] op_sel_hi:[1,0] neg_lo:[0,1] neg_hi:[0,1]
	v_mov_b32_e32 v20, v21
	v_mov_b32_e32 v21, v5
	v_mov_b32_e32 v25, v6
	v_pk_add_f32 v[6:7], v[20:21], v[24:25] neg_lo:[0,1] neg_hi:[0,1]
	v_mov_b32_e32 v16, v17
	v_mov_b32_e32 v17, v0
	v_pk_add_f32 v[0:1], v[16:17], v[6:7] neg_lo:[0,1] neg_hi:[0,1]
	v_mov_b32_e32 v22, v30
	v_pk_add_f32 v[16:17], v[22:23], v[0:1]
	v_mov_b32_e32 v31, v5
	v_pk_add_f32 v[6:7], v[16:17], v[16:17] op_sel:[0,1] op_sel_hi:[1,0]
	s_movk_i32 s6, 0x7ef
	v_pk_add_f32 v[20:21], v[4:5], v[6:7] op_sel:[1,0] op_sel_hi:[0,1]
	v_mov_b32_e32 v17, v20
	v_pk_add_f32 v[32:33], v[16:17], v[30:31] neg_lo:[0,1] neg_hi:[0,1]
	v_mov_b32_e32 v1, v6
	v_pk_add_f32 v[34:35], v[0:1], v[32:33] neg_lo:[0,1] neg_hi:[0,1]
	v_or_b32_e32 v13, 16, v116
	v_bitop3_b32 v0, v111, s6, 15 bitop3:0x6c
	v_cndmask_b32_e64 v2, v0, v13, s[0:1]
	v_or_b32_e32 v0, s18, v2
	v_mad_u64_u32 v[0:1], s[6:7], v0, s55, v[18:19]
	v_mad_i32_i24 v1, s19, v155, v1
	v_lshl_add_u64 v[4:5], v[0:1], 0, s[94:95]
	v_lshl_add_u64 v[4:5], v[4:5], 0, v[118:119]
	v_lshlrev_b32_e32 v2, 9, v2
	global_load_dword v24, v[4:5], off
	global_load_dword v23, v[4:5], off offset:128
	global_load_dword v22, v[4:5], off offset:1024
	global_load_dword v21, v[4:5], off offset:1152
	v_lshl_add_u64 v[4:5], s[4:5], 0, v[2:3]
	v_lshl_add_u64 v[0:1], v[0:1], 0, s[46:47]
	v_lshl_add_u64 v[4:5], v[4:5], 0, v[14:15]
	v_lshl_add_u64 v[0:1], v[0:1], 0, v[122:123]
	global_load_dwordx4 v[4:7], v[4:5], off
	s_nop 0
	global_load_dwordx3 v[0:2], v[0:1], off offset:2048
	v_sub_f32_e32 v16, v16, v32
	v_sub_f32_e32 v16, v30, v16
	v_add_f32_e32 v16, v34, v16
	v_add_f32_e32 v16, v16, v35
	v_add_f32_e32 v16, v20, v16
	v_cmp_nlt_f32_e32 vcc, 1.0, v36
	s_mov_b32 s6, 0x33800000
	v_add_u32_e32 v17, 1, v116
	v_cndmask_b32_e32 v16, v153, v16, vcc
	v_cmp_neq_f32_e32 vcc, 1.0, v36
	v_cvt_f32_ubyte0_e32 v17, v17
	v_bitop3_b32 v19, v111, 15, v111 bitop3:0xc
	v_cndmask_b32_e32 v16, v154, v16, vcc
	v_cmp_gt_f32_e32 vcc, s6, v36
	v_cvt_f32_ubyte0_e32 v19, v19
	s_mov_b32 s6, 0x3db504f3
	v_cndmask_b32_e64 v16, v16, -v36, vcc
	v_mul_f32_e32 v18, v16, v17
	v_mul_f32_e32 v18, 0x3fb8aa3b, v18
	v_mul_f32_e64 v17, -v16, v17
	v_mul_f32_e32 v19, v16, v19
	v_mul_f32_e32 v16, 0x41800000, v16
	v_mul_f32_e32 v17, 0x3fb8aa3b, v17
	v_mul_f32_e32 v16, 0x3fb8aa3b, v16
	v_exp_f32_e32 v124, v18
	v_mul_f32_e32 v19, 0x3fb8aa3b, v19
	v_exp_f32_e32 v126, v17
	v_exp_f32_e32 v128, v16
	s_waitcnt vmcnt(0)
	v_lshlrev_b32_e32 v16, 16, v37
	v_and_b32_e32 v17, 0xffff0000, v37
	s_waitcnt vmcnt(10)
	v_lshlrev_b32_e32 v30, 16, v38
	v_and_b32_e32 v31, 0xffff0000, v38
	v_exp_f32_e32 v117, v19
	s_waitcnt vmcnt(8)
	v_lshlrev_b32_e32 v34, 16, v40
	v_and_b32_e32 v35, 0xffff0000, v40
	v_lshlrev_b32_e32 v32, 16, v39
	v_and_b32_e32 v33, 0xffff0000, v39
	v_cmp_ne_u32_e32 vcc, 0, v116
	s_waitcnt vmcnt(6)
	v_mov_b32_e32 v37, v28
	v_mov_b32_e32 v28, v27
	v_mov_b32_e32 v36, v26
	v_pk_mul_f32 v[18:19], v[28:29], v[30:31]
	v_pk_mul_f32 v[26:27], v[34:35], s[6:7] op_sel_hi:[1,0]
	v_pk_fma_f32 v[18:19], v[36:37], v[16:17], v[18:19] neg_lo:[0,0,1] neg_hi:[0,0,1]
	v_pk_mul_f32 v[16:17], v[28:29], v[16:17]
	v_pk_mul_f32 v[18:19], v[124:125], v[18:19] op_sel_hi:[0,1]
	v_cvt_pk_bf16_f32 v20, v18, v19
	v_mul_u32_u24_e32 v19, 0x88, v116
	v_pk_fma_f32 v[16:17], v[36:37], v[30:31], v[16:17]
	v_lshl_add_u32 v18, v19, 1, 0
	v_pk_mul_f32 v[16:17], v[124:125], v[16:17] op_sel_hi:[0,1]
	v_lshl_add_u32 v121, v12, 1, v18
	v_cvt_pk_bf16_f32 v16, v16, v17
	ds_write2_b32 v121, v20, v16 offset1:32
	v_pk_mul_f32 v[16:17], v[32:33], s[6:7] op_sel_hi:[1,0]
	v_pk_mul_f32 v[30:31], v[28:29], v[26:27]
	v_add_u32_e32 v135, 0x1000, v121
	v_pk_fma_f32 v[30:31], v[36:37], v[16:17], v[30:31] neg_lo:[0,0,1] neg_hi:[0,0,1]
	v_pk_mul_f32 v[16:17], v[16:17], v[28:29]
	v_pk_mul_f32 v[32:33], v[126:127], v[30:31] op_sel_hi:[0,1]
	v_pk_fma_f32 v[16:17], v[26:27], v[36:37], v[16:17]
	v_cvt_pk_bf16_f32 v20, v32, v33
	v_pk_mul_f32 v[26:27], v[126:127], v[16:17] op_sel_hi:[0,1]
	v_cvt_pk_bf16_f32 v25, v26, v27
	ds_write2_b32 v135, v20, v25 offset0:64 offset1:96
	v_mul_f32_e32 v20, v117, v30
	v_cvt_pk_bf16_f32 v25, v20, s0
	v_lshl_or_b32 v20, v12, 4, v116
	v_lshl_add_u32 v136, v20, 1, 0
	v_mul_f32_e32 v16, v117, v16
	ds_write_b16 v136, v25 offset:8704
	v_mul_f32_e32 v25, v117, v31
	v_cvt_pk_bf16_f32 v16, v16, s0
	v_cvt_pk_bf16_f32 v25, v25, s0
	ds_write_b16 v136, v16 offset:10752
	v_mul_f32_e32 v16, v117, v17
	ds_write_b16 v136, v25 offset:8736
	v_cvt_pk_bf16_f32 v16, v16, s0
	v_cmp_eq_u32_e64 s[16:17], 0, v116
	v_lshl_add_u32 v25, v12, 2, 0
	ds_write_b16 v136, v16 offset:10784
	s_and_saveexec_b64 s[6:7], s[16:17]
	v_mov_b32_e32 v129, v128
	v_add_u32_e32 v16, 0x5000, v25
	ds_write2_b64 v16, v[128:129], v[128:129] offset1:32
	s_or_b64 exec, exec, s[6:7]
	s_movk_i32 s6, 0x78
	v_mad_u64_u32 v[16:17], s[6:7], v11, s6, v[116:117]
	v_lshl_add_u32 v137, v16, 1, 0
	ds_write_b16 v137, v8 offset:12800
	ds_write_b16_d16_hi v137, v8 offset:12840
	ds_write_b16 v137, v9 offset:12880
	ds_write_b16_d16_hi v137, v9 offset:12920
	ds_write_b16 v137, v10 offset:12960
	ds_write_b16_d16_hi v137, v10 offset:13000
	s_waitcnt vmcnt(0)
; template <int MODE>
; __device__ void scan_unit(int swave, const Params& p, int j, int b, int h, int dir, char* shm) {
;     ...
;   auto load_raw = [&](int c, Raw& R) {
;     const int tok = tokof(c, ti);
;     const bf16_t* row = P + (rowbase + tok) * LDP;
;     if (MODE == 0) {
;       R.q = *(const unsigned*)(row + E_GQ + h * 64 + dp); R.k = *(const unsigned*)(row + E_GK + h * 64 + dp);
;       const uint4* lrp = (const uint4*)(row + (dir ? E_GLB : E_GLF));
;       R.lr0 = lrp[0]; R.lr1 = lrp[1];
;       R.v = *(const uint2*)(row + E_GV + h * 128 + vg * 4);
;     } else if (MODE == 1) {
;       R.q = *(const unsigned*)(row + E_HQ + h * 64 + dp); R.k = *(const unsigned*)(row + (dir ? E_HZB : E_HZF) + h * 64 + dp);
;     ...
;       const float KSC = 0.08838834764831845f;
;       const float qx0 = lo_bf(R.q), qx1 = hi_bf(R.q), qy0 = lo_bf(R.q2), qy1 = hi_bf(R.q2);
;       const float kx0 = lo_bf(R.k) * KSC, kx1 = hi_bf(R.k) * KSC, ky0 = lo_bf(R.k2) * KSC, ky1 = hi_bf(R.k2) * KSC;
;       const float c0 = R.cs.x, sn0 = R.cs.y, c1 = R.cs.z, sn1 = R.cs.w;
;       const float qa0 = qx0 * c0 - qy0 * sn0, qb0 = qx0 * sn0 + qy0 * c0, qa1 = qx1 * c1 - qy1 * sn1, qb1 = qx1 * sn1 + qy1 * c1;
;       const float ka0 = kx0 * c0 - ky0 * sn0, kb0 = kx0 * sn0 + ky0 * c0, ka1 = kx1 * c1 - ky1 * sn1, kb1 = kx1 * sn1 + ky1 * c1;
;       const float ein = ret_ein, eti = ret_eti, eout = ret_eout;
;       *(unsigned*)(qin + ti * QS + dp) = pk2(qa0 * ein, qa1 * ein); *(unsigned*)(qin + ti * QS + 64 + dp) = pk2(qb0 * ein, qb1 * ein);
;       *(unsigned*)(ktil + ti * QS + dp) = pk2(ka0 * eti, ka1 * eti); *(unsigned*)(ktil + ti * QS + 64 + dp) = pk2(kb0 * eti, kb1 * eti);
;       koutT[dp * 16 + ti] = f2bf(ka0 * eout); koutT[(dp + 1) * 16 + ti] = f2bf(ka1 * eout);
;       koutT[(64 + dp) * 16 + ti] = f2bf(kb0 * eout); koutT[(65 + dp) * 16 + ti] = f2bf(kb1 * eout);
;       if (ti == 0) { const float dd = ret_dd; *(float2*)(dec + dp) = make_float2(dd, dd); *(float2*)(dec + 64 + dp) = make_float2(dd, dd); }
;       const int c6 = vg * 6;
;       vT[(c6 + 0) * VS + ti] = (bf16_t)(R.v30 & 0xffff); vT[(c6 + 1) * VS + ti] = (bf16_t)(R.v30 >> 16);
;       vT[(c6 + 2) * VS + ti] = (bf16_t)(R.v31 & 0xffff); vT[(c6 + 3) * VS + ti] = (bf16_t)(R.v31 >> 16);
;       vT[(c6 + 4) * VS + ti] = (bf16_t)(R.v32 & 0xffff); vT[(c6 + 5) * VS + ti] = (bf16_t)(R.v32 >> 16);
	v_lshlrev_b32_e32 v10, 16, v23
	v_and_b32_e32 v11, 0xffff0000, v23
	s_waitcnt vmcnt(1)
	v_mov_b32_e32 v29, v6
	v_mov_b32_e32 v6, v5
	v_lshlrev_b32_e32 v8, 16, v24
	v_and_b32_e32 v9, 0xffff0000, v24
	v_mov_b32_e32 v28, v4
	v_pk_mul_f32 v[4:5], v[6:7], v[10:11]
	v_mov_b32_e32 v125, v124
	v_pk_fma_f32 v[4:5], v[28:29], v[8:9], v[4:5] neg_lo:[0,0,1] neg_hi:[0,0,1]
	v_lshlrev_b32_e32 v26, 16, v22
	v_pk_mul_f32 v[4:5], v[124:125], v[4:5]
	v_and_b32_e32 v27, 0xffff0000, v22
	v_cvt_pk_bf16_f32 v17, v4, v5
	v_pk_mul_f32 v[4:5], v[6:7], v[8:9]
	v_lshlrev_b32_e32 v22, 16, v21
	v_pk_fma_f32 v[4:5], v[28:29], v[10:11], v[4:5]
	v_and_b32_e32 v23, 0xffff0000, v21
	v_pk_mul_f32 v[4:5], v[124:125], v[4:5]
	s_mov_b32 s6, 0x3db504f3
	v_cvt_pk_bf16_f32 v4, v4, v5
	v_add_u32_e32 v139, 0x5000, v121
	v_pk_mul_f32 v[8:9], v[22:23], s[6:7] op_sel_hi:[1,0]
	ds_write2_b32 v139, v17, v4 offset0:128 offset1:160
	v_pk_mul_f32 v[4:5], v[26:27], s[6:7] op_sel_hi:[1,0]
	v_pk_mul_f32 v[10:11], v[6:7], v[8:9]
	v_mov_b32_e32 v127, v126
	v_pk_fma_f32 v[10:11], v[28:29], v[4:5], v[10:11] neg_lo:[0,0,1] neg_hi:[0,0,1]
	v_pk_mul_f32 v[4:5], v[4:5], v[6:7]
	v_pk_mul_f32 v[22:23], v[126:127], v[10:11]
	v_pk_fma_f32 v[4:5], v[8:9], v[28:29], v[4:5]
	v_cvt_pk_bf16_f32 v17, v22, v23
	v_pk_mul_f32 v[6:7], v[126:127], v[4:5]
	v_add_u32_e32 v140, 0x6000, v121
	v_cvt_pk_bf16_f32 v6, v6, v7
	ds_write2_b32 v140, v17, v6 offset0:192 offset1:224
	v_mul_f32_e32 v6, v117, v10
	v_mul_f32_e32 v4, v117, v4
	v_cvt_pk_bf16_f32 v6, v6, s0
	v_cvt_pk_bf16_f32 v4, v4, s0
	ds_write_b16 v136, v6 offset:29696
	v_mul_f32_e32 v6, v117, v11
	ds_write_b16 v136, v4 offset:31744
	v_mul_f32_e32 v4, v117, v5
	v_cvt_pk_bf16_f32 v6, v6, s0
	v_cvt_pk_bf16_f32 v4, v4, s0
	ds_write_b16 v136, v6 offset:29728
	ds_write_b16 v136, v4 offset:31776
	s_and_saveexec_b64 s[6:7], vcc
	s_xor_b64 s[6:7], exec, s[6:7]
	s_mov_b32 s39, 0x2aaaaaab
	s_movk_i32 s40, 0xff40
	s_movk_i32 s41, 0xff
	s_or_saveexec_b64 s[6:7], s[6:7]
	s_lshl_b32 s8, s8, 7
	s_xor_b64 exec, exec, s[6:7]
	v_mov_b32_e32 v129, v128
	v_add_u32_e32 v4, 0xa000, v25
	ds_write2_b64 v4, v[128:129], v[128:129] offset0:64 offset1:96
	s_or_b64 exec, exec, s[6:7]
	v_readlane_b32 s12, v248, 8
	v_readlane_b32 s14, v248, 10
	v_readlane_b32 s15, v248, 11
	s_add_u32 s6, s14, s2
	s_addc_u32 s7, s15, s3
	s_and_b64 s[2:3], s[0:1], exec
	s_cselect_b32 s2, 0, 0x3000000
	s_add_u32 s2, s6, s2
	v_ashrrev_i32_e32 v4, 6, v111
	v_lshrrev_b32_e32 v5, 31, v111
	s_addc_u32 s3, s7, 0
	v_add_u32_e32 v5, v4, v5
	s_add_u32 s2, s2, s46
	s_waitcnt vmcnt(0)
	ds_write_b16 v137, v0 offset:33792
	ds_write_b16_d16_hi v137, v0 offset:33832
	ds_write_b16 v137, v1 offset:33872
	ds_write_b16_d16_hi v137, v1 offset:33912
	ds_write_b16 v137, v2 offset:33952
	ds_write_b16_d16_hi v137, v2 offset:33992
	v_or_b32_e32 v23, 32, v116
	v_xor_b32_e32 v0, 0x7df, v116
	v_lshrrev_b32_e32 v21, 1, v5
	v_and_b32_e32 v5, -2, v5
	s_addc_u32 s3, s3, 0
	v_cndmask_b32_e64 v2, v0, v23, s[0:1]
	v_sub_u32_e32 v22, v4, v5
	s_add_u32 s42, s2, 0x4000000
	v_or_b32_e32 v4, s18, v2
	v_mov_b64_e32 v[0:1], s[44:45]
	s_addc_u32 s43, s3, 0
	v_mad_u64_u32 v[4:5], s[2:3], v4, s55, v[0:1]
	v_mad_i32_i24 v5, s19, v155, v5
	s_lshl_b32 s94, s8, 1
	v_lshl_add_u64 v[6:7], v[4:5], 0, s[94:95]
	s_mov_b32 s48, s46
	s_mov_b32 s49, s95
	v_lshl_add_u64 v[6:7], v[6:7], 0, v[118:119]
	v_lshlrev_b32_e32 v2, 9, v2
	global_load_dword v242, v[6:7], off
	global_load_dword v241, v[6:7], off offset:128
	global_load_dword v240, v[6:7], off offset:1024
	global_load_dword v239, v[6:7], off offset:1152
	v_lshl_add_u64 v[6:7], s[4:5], 0, v[2:3]
	v_lshl_add_u64 v[4:5], v[4:5], 0, s[48:49]
	v_lshl_add_u64 v[6:7], v[6:7], 0, v[14:15]
	v_lshl_add_u64 v[4:5], v[4:5], 0, v[122:123]
	global_load_dwordx4 v[8:11], v[6:7], off
	global_load_dwordx3 v[112:114], v[4:5], off offset:2048
	v_or_b32_e32 v2, 48, v116
	v_xor_b32_e32 v4, 0x7cf, v116
	v_cndmask_b32_e64 v2, v4, v2, s[0:1]
	v_or_b32_e32 v4, s18, v2
	v_mad_u64_u32 v[0:1], s[2:3], v4, s55, v[0:1]
	v_mad_i32_i24 v1, s19, v155, v1
	v_lshl_add_u64 v[4:5], v[0:1], 0, s[94:95]
	v_lshl_add_u64 v[4:5], v[4:5], 0, v[118:119]
	v_lshlrev_b32_e32 v2, 9, v2
	global_load_dword v238, v[4:5], off
	global_load_dword v237, v[4:5], off offset:128
	global_load_dword v236, v[4:5], off offset:1024
	global_load_dword v235, v[4:5], off offset:1152
	v_lshl_add_u64 v[4:5], s[4:5], 0, v[2:3]
	v_lshl_add_u64 v[4:5], v[4:5], 0, v[14:15]
	v_lshl_add_u64 v[0:1], v[0:1], 0, s[48:49]
	v_lshl_add_u64 v[0:1], v[0:1], 0, v[122:123]
	global_load_dwordx4 v[4:7], v[4:5], off
	s_nop 0
	global_load_dwordx3 v[108:110], v[0:1], off offset:2048
	v_lshlrev_b32_e32 v1, 1, v19
	v_readlane_b32 s2, v247, 30
	v_bfe_u32 v17, v111, 4, 2
	v_lshlrev_b32_e32 v0, 2, v12
	v_add_u32_e32 v2, s2, v1
	v_readlane_b32 s2, v247, 32
	v_readlane_b32 s20, v247, 33
	v_add_u32_e32 v141, 0, v0
	v_add_u32_e32 v144, s2, v0
	v_add_u32_e32 v145, s20, v0
	v_lshlrev_b32_e32 v0, 2, v17
	v_readlane_b32 s13, v248, 9
	v_lshl_add_u64 v[130:131], s[4:5], 0, v[14:15]
	v_or_b32_e32 v15, 2, v0
	v_cmp_gt_u32_e64 s[12:13], v15, v116
	v_or_b32_e32 v15, 3, v0
	v_readlane_b32 s21, v247, 34
	v_cmp_gt_u32_e64 s[8:9], v0, v116
	v_cmp_lt_u32_e64 s[10:11], v0, v116
	v_cmp_gt_u32_e64 s[14:15], v15, v116
	v_mul_lo_u32 v15, v21, 48
	v_lshl_or_b32 v0, v22, 4, v0
	s_movk_i32 s2, 0xc4
	v_lshl_add_u32 v142, v12, 1, v2
	v_readlane_b32 s3, v247, 31
	v_lshl_add_u32 v159, v16, 1, s21
	v_lshlrev_b32_e32 v12, 3, v17
	v_lshlrev_b32_e32 v14, 4, v17
	v_or_b32_e32 v16, v15, v116
	v_add_u32_e32 v13, v15, v13
	v_add_u32_e32 v15, v15, v23
	v_mul_lo_u32 v0, v0, s2
	v_lshlrev_b32_e32 v31, 5, v116
	v_lshl_add_u32 v143, v20, 1, s3
	v_add_lshl_u32 v19, v0, v16, 1
	v_readlane_b32 s2, v247, 35
	v_add_u32_e32 v20, 0xc4, v0
	v_add_u32_e32 v23, 0x188, v0
	v_add_u32_e32 v25, 0x24c, v0
	v_add_lshl_u32 v27, v0, v13, 1
	v_add_lshl_u32 v0, v0, v15, 1
	v_lshl_or_b32 v31, v22, 11, v31
	v_readlane_b32 s25, v247, 36
	v_readlane_b32 s28, v247, 37
	v_add_u32_e32 v203, v2, v14
	v_add_u32_e32 v2, s21, v12
	v_readlane_b32 s21, v247, 38
	s_waitcnt lgkmcnt(0)
	s_barrier
; template <int MODE>
; __device__ void scan_unit(int swave, const Params& p, int j, int b, int h, int dir, char* shm) {
;     ...
;   f32x4 S[4][NVT];
; #pragma unroll
;   for (int a = 0; a < 4; ++a)
; #pragma unroll
;     for (int t = 0; t < NVT; ++t) S[a][t] = (f32x4){0.f, 0.f, 0.f, 0.f};
;   auto compute = [&](const char* buf, bf16_t* obuf) {
;     const bf16_t* qin = (const bf16_t*)buf; const bf16_t* ktil = (const bf16_t*)(buf + OFF_KT); const bf16_t* koutT = (const bf16_t*)(buf + OFF_KO);
;     const bf16_t* vT = (const bf16_t*)(buf + OFF_VT); const float* dec = (const float*)(buf + OFF_DEC);
;     bf16x8 Asc = {0, 0, 0, 0, 0, 0, 0, 0};
;     if (KS == 1 || wk == 0) {
;       f32x4 sc = {0.f, 0.f, 0.f, 0.f};
; #pragma unroll
;       for (int m = 0; m < DK / 32; ++m) {
;         const bf16x8 a = *(const bf16x8*)(ktil + r * QS + m * 32 + q4 * 8);
;         const bf16x8 bb = *(const bf16x8*)(qin + r * QS + m * 32 + q4 * 8);
;         sc = __builtin_amdgcn_mfma_f32_16x16x32_bf16(a, bb, sc, 0, 0, 0);
;       }
;       {
;         const unsigned p01 = pk2(q4 * 4 + 0 > r ? 0.f : sc[0], q4 * 4 + 1 > r ? 0.f : sc[1]);
;         const unsigned p23 = pk2(q4 * 4 + 2 > r ? 0.f : sc[2], q4 * 4 + 3 > r ? 0.f : sc[3]);
;         Asc[0] = (short)(p01 & 0xffff); Asc[1] = (short)(p01 >> 16); Asc[2] = (short)(p23 & 0xffff); Asc[3] = (short)(p23 >> 16);
;       }
;     }
;     bf16x8 Bv[NVT];
; #pragma unroll
;     for (int t = 0; t < NVT; ++t) {
;       const uint2 vv = *(const uint2*)(vT + ((vt0 + t) * 16 + r) * VS + q4 * 4);
;       Bv[t] = (bf16x8){(short)(vv.x & 0xffff), (short)(vv.x >> 16), (short)(vv.y & 0xffff), (short)(vv.y >> 16), 0, 0, 0, 0};
;     }
;     bf16x8 Aq[2];
; #pragma unroll
;     for (int m = 0; m < 2; ++m) {
;       const uint2 lo = *(const uint2*)(qin + r * QS + slab + (2 * m) * 16 + q4 * 4);
;       const uint2 hi = *(const uint2*)(qin + r * QS + slab + (2 * m + 1) * 16 + q4 * 4);
;       Aq[m] = (bf16x8){(short)(lo.x & 0xffff), (short)(lo.x >> 16), (short)(lo.y & 0xffff), (short)(lo.y >> 16),
;                        (short)(hi.x & 0xffff), (short)(hi.x >> 16), (short)(hi.y & 0xffff), (short)(hi.y >> 16)};
;     }
;     f32x4 o[NVT];
; #pragma unroll
;     for (int t = 0; t < NVT; ++t) {
;       o[t] = (f32x4){0.f, 0.f, 0.f, 0.f};
;       if (KS == 1 || wk == 0) o[t] = __builtin_amdgcn_mfma_f32_16x16x32_bf16(Asc, Bv[t], o[t], 0, 0, 0);
;     }
	v_lshlrev_b32_e32 v17, 7, v22
	v_add_lshl_u32 v21, v20, v16, 1
	v_add_lshl_u32 v28, v20, v13, 1
	v_add_u32_e32 v169, s2, v0
	v_add_lshl_u32 v20, v20, v15, 1
	v_add_u32_e32 v186, s25, v0
	v_add_u32_e32 v199, s28, v0
	v_add_u32_e32 v215, s21, v0
	v_add3_u32 v0, s3, v12, v31
	v_cmp_eq_u32_e64 s[6:7], 0, v22
	v_add_u32_e32 v160, v18, v14
	v_add_u32_e32 v18, 0, v17
	v_add_lshl_u32 v24, v23, v16, 1
	v_add_lshl_u32 v26, v25, v16, 1
	v_add_lshl_u32 v29, v23, v13, 1
	v_add_lshl_u32 v30, v25, v13, 1
	v_add_u32_e32 v170, s2, v20
	v_add_lshl_u32 v23, v23, v15, 1
	v_add_lshl_u32 v25, v25, v15, 1
	v_add_u32_e32 v32, 0, v12
	v_lshlrev_b32_e32 v22, 8, v22
	v_mul_lo_u32 v16, v16, 40
	v_mul_lo_u32 v13, v13, 40
	v_mul_lo_u32 v15, v15, 40
	v_add_u32_e32 v187, s25, v20
	v_add_u32_e32 v200, s28, v20
	v_add_u32_e32 v216, s21, v20
	v_add_u32_e32 v221, 0x200, v0
	v_add_u32_e32 v222, 0x400, v0
	v_add_u32_e32 v223, 0x600, v0
	v_lshlrev_b32_e32 v0, 3, v111
	v_mov_b32_e32 v20, 0
	s_mov_b32 s24, 0
	v_mov_b32_e32 v129, v128
	v_cmp_gt_i32_e64 s[4:5], s52, v111
	v_add_u32_e32 v161, s2, v19
	v_add_u32_e32 v162, s2, v21
	v_add_u32_e32 v163, s2, v24
	v_add_u32_e32 v164, s2, v26
	v_add_u32_e32 v165, s2, v27
	v_add_u32_e32 v166, s2, v28
	v_add_u32_e32 v167, s2, v29
	v_add_u32_e32 v168, s2, v30
	v_add_u32_e32 v171, s2, v23
	v_add_u32_e32 v172, s2, v25
	v_add_u32_e32 v173, v32, v31
	v_add3_u32 v174, 0, v22, v14
	v_add_u32_e32 v175, v32, v16
	v_add_u32_e32 v176, v32, v13
	v_add_u32_e32 v177, v32, v15
	v_add_u32_e32 v178, s25, v19
	v_add_u32_e32 v179, s25, v21
	v_add_u32_e32 v180, s25, v24
	v_add_u32_e32 v181, s25, v26
	v_add_u32_e32 v182, s25, v27
	v_add_u32_e32 v183, s25, v28
	v_add_u32_e32 v184, s25, v29
	v_add_u32_e32 v185, s25, v30
	v_add_u32_e32 v188, s25, v23
	v_add_u32_e32 v189, s25, v25
	v_add3_u32 v190, v18, v17, v14
	v_add_u32_e32 v191, s28, v19
	v_add_u32_e32 v192, s28, v21
	v_add_u32_e32 v193, s28, v24
	v_add_u32_e32 v194, s28, v26
	v_add_u32_e32 v195, s28, v27
	v_add_u32_e32 v196, s28, v28
	v_add_u32_e32 v197, s28, v29
	v_add_u32_e32 v198, s28, v30
	v_add_u32_e32 v201, s28, v23
	v_add_u32_e32 v202, s28, v25
	v_add_u32_e32 v204, v2, v16
	v_add_u32_e32 v205, v2, v13
	v_add_u32_e32 v206, v2, v15
	v_add_u32_e32 v207, s21, v19
	v_add_u32_e32 v208, s21, v21
	v_add_u32_e32 v209, s21, v24
	v_add_u32_e32 v210, s21, v26
	v_add_u32_e32 v211, s21, v27
	v_add_u32_e32 v212, s21, v28
	v_add_u32_e32 v213, s21, v29
	v_add_u32_e32 v214, s21, v30
	v_add_u32_e32 v217, s21, v23
	v_add_u32_e32 v218, s21, v25
	v_add3_u32 v219, s3, v31, v12
	v_add3_u32 v220, s20, v22, v14
	v_add3_u32 v224, v18, v1, v12
	v_add_u32_e32 v138, s28, v0
	v_add_u32_e32 v115, s21, v0
	v_add_u32_e32 v225, s2, v0
	v_add_u32_e32 v226, s25, v0
	v_mov_b32_e32 v21, v20
	v_mov_b32_e32 v22, v20
	v_mov_b32_e32 v23, v20
	v_mov_b32_e32 v32, v20
	v_mov_b32_e32 v33, v20
	v_mov_b32_e32 v34, v20
	v_mov_b32_e32 v35, v20
	v_mov_b32_e32 v36, v20
	v_mov_b32_e32 v37, v20
	v_mov_b32_e32 v38, v20
	v_mov_b32_e32 v39, v20
	v_mov_b32_e32 v44, v20
	v_mov_b32_e32 v45, v20
	v_mov_b32_e32 v46, v20
	v_mov_b32_e32 v47, v20
	v_mov_b32_e32 v48, v20
	v_mov_b32_e32 v49, v20
	v_mov_b32_e32 v50, v20
	v_mov_b32_e32 v51, v20
	v_mov_b32_e32 v52, v20
	v_mov_b32_e32 v53, v20
	v_mov_b32_e32 v54, v20
	v_mov_b32_e32 v55, v20
	v_mov_b32_e32 v56, v20
	v_mov_b32_e32 v57, v20
	v_mov_b32_e32 v58, v20
	v_mov_b32_e32 v59, v20
	v_mov_b32_e32 v60, v20
	v_mov_b32_e32 v61, v20
	v_mov_b32_e32 v62, v20
	v_mov_b32_e32 v63, v20
	v_mov_b32_e32 v64, v20
	v_mov_b32_e32 v65, v20
	v_mov_b32_e32 v66, v20
	v_mov_b32_e32 v67, v20
	v_mov_b32_e32 v40, v20
	v_mov_b32_e32 v41, v20
	v_mov_b32_e32 v42, v20
	v_mov_b32_e32 v43, v20
	v_mov_b32_e32 v28, v20
	v_mov_b32_e32 v29, v20
	v_mov_b32_e32 v30, v20
	v_mov_b32_e32 v31, v20
	v_mov_b32_e32 v24, v20
	v_mov_b32_e32 v25, v20
	v_mov_b32_e32 v26, v20
	v_mov_b32_e32 v27, v20
	s_waitcnt vmcnt(1)
	v_mov_b32_e32 v70, v4
	v_mov_b32_e32 v71, v6
	v_mov_b32_e32 v6, v5
	v_add_u32_e32 v227, 32, v143
	v_add_u32_e32 v228, 0x800, v143
	v_add_u32_e32 v229, 0x820, v143
	v_add_u32_e32 v230, 40, v159
	v_add_u32_e32 v231, 0x50, v159
	v_add_u32_e32 v232, 0x78, v159
	v_add_u32_e32 v233, 0xa0, v159
	v_add_u32_e32 v234, 0xc8, v159
	v_mov_b32_e32 v68, v113
	v_mov_b32_e32 v69, v114
	s_waitcnt vmcnt(0)
	v_mov_b32_e32 v0, v109
	v_mov_b32_e32 v1, v110
	v_lshlrev_b32_e32 v120, 2, v111
	s_branch .LBB0_571
